# guepi
# speedup vs baseline: 1.0178x; 1.0018x over previous
; __device__ __forceinline__ float silu_f(float x) { return x * __builtin_amdgcn_rcpf(1.f + __builtin_amdgcn_exp2f(-1.4426950408889634f * x)); }
; template <int EPI>
; __device__ __forceinline__ void gemm_epi(const GemmArgs& G, const f32x4 (&a)[4][2], int rbase, int cbase, int fq, const float (&ssv)[4]) {
;   const int tn = cbase >> 8;
; #pragma unroll
;   for (int m = 0; m < 4; ++m) {
;     const int row = rbase + m * 16;
;     float rs = 1.f;
;     if constexpr (EPI == EPI_GU || EPI == EPI_EVIN || EPI == EPI_ODIN) rs = rsqrtf(ssv[m] * (1.f / 2048.f) + 1e-6f);
;     if constexpr (EPI == EPI_GU) {
;       const f32x4 gv = a[m][0] * rs, uv = a[m][1] * rs;
;       const int hc = (cbase >> 1) + fq * 4;
;       u32x2 o = {cvtpk(silu_f(gv[0]) * uv[0], silu_f(gv[1]) * uv[1]), cvtpk(silu_f(gv[2]) * uv[2], silu_f(gv[3]) * uv[3])};
;       *reinterpret_cast<u32x2*>(G.d0 + (size_t)(row - G.row0) * DFF + hc) = o;
.LBB0_2558:
	v_readfirstlane_b32 s16, v224
	s_andn2_b32 s16, s16, 63
	s_nop 0
	v_add_u32_e32 v128, s16, v225
	v_mov_b32_e32 v158, 0xbfb8aa3b
	v_and_b32_e32 v129, 15, v128
	v_ashrrev_i32_e32 v135, 2, v128
	v_and_or_b32 v129, v135, 64, v129
	v_lshrrev_b32_e32 v135, 1, v128
	v_and_b32_e32 v135, 0x60, v135
	v_or_b32_e32 v136, s29, v135
	v_lshrrev_b32_e32 v128, 2, v128
	v_ashrrev_i32_e32 v140, 1, v136
	v_and_b32_e32 v136, 12, v128
	v_or_b32_e32 v140, v140, v136
	v_add_u32_e32 v144, s28, v129
	v_subrev_u32_e32 v141, s40, v144
	v_mul_u32_u24_e32 v141, 0x2c00, v141
	v_lshl_add_u32 v141, v140, 1, v141
	v_mov_b32_e32 v160, 1.0
	s_waitcnt vmcnt(8)
	v_fmamk_f32 v162, v139, 0x3a000000, v229
	v_fmamk_f32 v164, v138, 0x3a000000, v229
	v_fmamk_f32 v166, v137, 0x3a000000, v229
	v_fmamk_f32 v168, v134, 0x3a000000, v229
	v_fmamk_f32 v170, v133, 0x3a000000, v229
	v_fmamk_f32 v172, v132, 0x3a000000, v229
	v_fmamk_f32 v174, v131, 0x3a000000, v229
	v_fmamk_f32 v176, v130, 0x3a000000, v229
	v_rsq_f32_e32 v162, v162
	v_rsq_f32_e32 v164, v164
	v_rsq_f32_e32 v166, v166
	v_rsq_f32_e32 v168, v168
	v_rsq_f32_e32 v170, v170
	v_rsq_f32_e32 v172, v172
	v_rsq_f32_e32 v174, v174
	v_rsq_f32_e32 v176, v176
	v_pk_mul_f32 v[120:121], v[162:163], v[120:121] op_sel_hi:[0,1]
	v_pk_mul_f32 v[112:113], v[164:165], v[112:113] op_sel_hi:[0,1]
	v_pk_mul_f32 v[122:123], v[162:163], v[122:123] op_sel_hi:[0,1]
	v_pk_mul_f32 v[114:115], v[164:165], v[114:115] op_sel_hi:[0,1]
	v_pk_mul_f32 v[124:125], v[162:163], v[124:125] op_sel_hi:[0,1]
	v_pk_mul_f32 v[116:117], v[164:165], v[116:117] op_sel_hi:[0,1]
	v_pk_mul_f32 v[126:127], v[162:163], v[126:127] op_sel_hi:[0,1]
	v_pk_mul_f32 v[118:119], v[164:165], v[118:119] op_sel_hi:[0,1]
	v_pk_mul_f32 v[182:183], v[158:159], v[120:121] op_sel_hi:[0,1]
	v_pk_mul_f32 v[186:187], v[158:159], v[112:113] op_sel_hi:[0,1]
	v_pk_mul_f32 v[184:185], v[158:159], v[122:123] op_sel_hi:[0,1]
	v_pk_mul_f32 v[188:189], v[158:159], v[114:115] op_sel_hi:[0,1]
	v_exp_f32_e32 v182, v182
	v_exp_f32_e32 v186, v186
	v_exp_f32_e32 v183, v183
	v_exp_f32_e32 v187, v187
	v_exp_f32_e32 v184, v184
	v_exp_f32_e32 v188, v188
	v_exp_f32_e32 v185, v185
	v_exp_f32_e32 v189, v189
	v_pk_add_f32 v[182:183], v[160:161], v[182:183] op_sel_hi:[0,1]
	v_pk_add_f32 v[186:187], v[160:161], v[186:187] op_sel_hi:[0,1]
	v_pk_add_f32 v[184:185], v[160:161], v[184:185] op_sel_hi:[0,1]
	v_pk_add_f32 v[188:189], v[160:161], v[188:189] op_sel_hi:[0,1]
	v_rcp_f32_e32 v182, v182
	v_rcp_f32_e32 v186, v186
	v_rcp_f32_e32 v183, v183
	v_rcp_f32_e32 v187, v187
	v_rcp_f32_e32 v184, v184
	v_rcp_f32_e32 v188, v188
	v_rcp_f32_e32 v185, v185
	v_rcp_f32_e32 v189, v189
	v_pk_mul_f32 v[120:121], v[120:121], v[182:183]
	v_pk_mul_f32 v[112:113], v[112:113], v[186:187]
	v_pk_mul_f32 v[122:123], v[122:123], v[184:185]
	v_pk_mul_f32 v[114:115], v[114:115], v[188:189]
	v_pk_mul_f32 v[120:121], v[124:125], v[120:121]
	v_pk_mul_f32 v[112:113], v[116:117], v[112:113]
	v_pk_mul_f32 v[122:123], v[126:127], v[122:123]
	v_pk_mul_f32 v[114:115], v[118:119], v[114:115]
	v_cvt_pk_bf16_f32 v200, v120, v121
	v_cvt_pk_bf16_f32 v202, v112, v113
	v_cvt_pk_bf16_f32 v201, v122, v123
	v_cvt_pk_bf16_f32 v203, v114, v115
	v_mov_b32_e32 v210, v141
	v_add_u32_e32 v211, 0x2c000, v141
	global_store_dwordx2 v210, v[200:201], s[10:11]
	global_store_dwordx2 v211, v[202:203], s[10:11]
	v_pk_mul_f32 v[104:105], v[166:167], v[104:105] op_sel_hi:[0,1]
	v_pk_mul_f32 v[96:97], v[168:169], v[96:97] op_sel_hi:[0,1]
	v_pk_mul_f32 v[106:107], v[166:167], v[106:107] op_sel_hi:[0,1]
	v_pk_mul_f32 v[98:99], v[168:169], v[98:99] op_sel_hi:[0,1]
	v_pk_mul_f32 v[108:109], v[166:167], v[108:109] op_sel_hi:[0,1]
	v_pk_mul_f32 v[100:101], v[168:169], v[100:101] op_sel_hi:[0,1]
	v_pk_mul_f32 v[110:111], v[166:167], v[110:111] op_sel_hi:[0,1]
	v_pk_mul_f32 v[102:103], v[168:169], v[102:103] op_sel_hi:[0,1]
	v_pk_mul_f32 v[190:191], v[158:159], v[104:105] op_sel_hi:[0,1]
	v_pk_mul_f32 v[194:195], v[158:159], v[96:97] op_sel_hi:[0,1]
	v_pk_mul_f32 v[192:193], v[158:159], v[106:107] op_sel_hi:[0,1]
	v_pk_mul_f32 v[196:197], v[158:159], v[98:99] op_sel_hi:[0,1]
	v_exp_f32_e32 v190, v190
	v_exp_f32_e32 v194, v194
	v_exp_f32_e32 v191, v191
	v_exp_f32_e32 v195, v195
	v_exp_f32_e32 v192, v192
	v_exp_f32_e32 v196, v196
	v_exp_f32_e32 v193, v193
	v_exp_f32_e32 v197, v197
	v_pk_add_f32 v[190:191], v[160:161], v[190:191] op_sel_hi:[0,1]
	v_pk_add_f32 v[194:195], v[160:161], v[194:195] op_sel_hi:[0,1]
	v_pk_add_f32 v[192:193], v[160:161], v[192:193] op_sel_hi:[0,1]
	v_pk_add_f32 v[196:197], v[160:161], v[196:197] op_sel_hi:[0,1]
	v_rcp_f32_e32 v190, v190
	v_rcp_f32_e32 v194, v194
	v_rcp_f32_e32 v191, v191
	v_rcp_f32_e32 v195, v195
	v_rcp_f32_e32 v192, v192
	v_rcp_f32_e32 v196, v196
	v_rcp_f32_e32 v193, v193
	v_rcp_f32_e32 v197, v197
	v_pk_mul_f32 v[104:105], v[104:105], v[190:191]
	v_pk_mul_f32 v[96:97], v[96:97], v[194:195]
	v_pk_mul_f32 v[106:107], v[106:107], v[192:193]
	v_pk_mul_f32 v[98:99], v[98:99], v[196:197]
	v_pk_mul_f32 v[104:105], v[108:109], v[104:105]
	v_pk_mul_f32 v[96:97], v[100:101], v[96:97]
	v_pk_mul_f32 v[106:107], v[110:111], v[106:107]
	v_pk_mul_f32 v[98:99], v[102:103], v[98:99]
	v_cvt_pk_bf16_f32 v204, v104, v105
	v_cvt_pk_bf16_f32 v206, v96, v97
	v_cvt_pk_bf16_f32 v205, v106, v107
	v_cvt_pk_bf16_f32 v207, v98, v99
	v_add_u32_e32 v212, 0x58000, v141
	v_add_u32_e32 v213, 0x84000, v141
	global_store_dwordx2 v212, v[204:205], s[10:11]
	global_store_dwordx2 v213, v[206:207], s[10:11]
	v_pk_mul_f32 v[88:89], v[162:163], v[88:89] op_sel_hi:[0,1]
	v_pk_mul_f32 v[80:81], v[164:165], v[80:81] op_sel_hi:[0,1]
	v_pk_mul_f32 v[90:91], v[162:163], v[90:91] op_sel_hi:[0,1]
; __device__ __forceinline__ float silu_f(float x) { return x * __builtin_amdgcn_rcpf(1.f + __builtin_amdgcn_exp2f(-1.4426950408889634f * x)); }
; template <int EPI>
; __device__ __forceinline__ void gemm_epi(const GemmArgs& G, const f32x4 (&a)[4][2], int rbase, int cbase, int fq, const float (&ssv)[4]) {
;     ...
;     if constexpr (EPI == EPI_GU || EPI == EPI_EVIN || EPI == EPI_ODIN) rs = rsqrtf(ssv[m] * (1.f / 2048.f) + 1e-6f);
;     if constexpr (EPI == EPI_GU) {
;       const f32x4 gv = a[m][0] * rs, uv = a[m][1] * rs;
;       const int hc = (cbase >> 1) + fq * 4;
;       u32x2 o = {cvtpk(silu_f(gv[0]) * uv[0], silu_f(gv[1]) * uv[1]), cvtpk(silu_f(gv[2]) * uv[2], silu_f(gv[3]) * uv[3])};
;       *reinterpret_cast<u32x2*>(G.d0 + (size_t)(row - G.row0) * DFF + hc) = o;
	v_pk_mul_f32 v[82:83], v[164:165], v[82:83] op_sel_hi:[0,1]
	v_pk_mul_f32 v[92:93], v[162:163], v[92:93] op_sel_hi:[0,1]
	v_pk_mul_f32 v[84:85], v[164:165], v[84:85] op_sel_hi:[0,1]
	v_pk_mul_f32 v[94:95], v[162:163], v[94:95] op_sel_hi:[0,1]
	v_pk_mul_f32 v[86:87], v[164:165], v[86:87] op_sel_hi:[0,1]
	v_pk_mul_f32 v[182:183], v[158:159], v[88:89] op_sel_hi:[0,1]
	v_pk_mul_f32 v[186:187], v[158:159], v[80:81] op_sel_hi:[0,1]
	v_pk_mul_f32 v[184:185], v[158:159], v[90:91] op_sel_hi:[0,1]
	v_pk_mul_f32 v[188:189], v[158:159], v[82:83] op_sel_hi:[0,1]
	v_exp_f32_e32 v182, v182
	v_exp_f32_e32 v186, v186
	v_exp_f32_e32 v183, v183
	v_exp_f32_e32 v187, v187
	v_exp_f32_e32 v184, v184
	v_exp_f32_e32 v188, v188
	v_exp_f32_e32 v185, v185
	v_exp_f32_e32 v189, v189
	v_pk_add_f32 v[182:183], v[160:161], v[182:183] op_sel_hi:[0,1]
	v_pk_add_f32 v[186:187], v[160:161], v[186:187] op_sel_hi:[0,1]
	v_pk_add_f32 v[184:185], v[160:161], v[184:185] op_sel_hi:[0,1]
	v_pk_add_f32 v[188:189], v[160:161], v[188:189] op_sel_hi:[0,1]
	v_rcp_f32_e32 v182, v182
	v_rcp_f32_e32 v186, v186
	v_rcp_f32_e32 v183, v183
	v_rcp_f32_e32 v187, v187
	v_rcp_f32_e32 v184, v184
	v_rcp_f32_e32 v188, v188
	v_rcp_f32_e32 v185, v185
	v_rcp_f32_e32 v189, v189
	v_pk_mul_f32 v[88:89], v[88:89], v[182:183]
	v_pk_mul_f32 v[80:81], v[80:81], v[186:187]
	v_pk_mul_f32 v[90:91], v[90:91], v[184:185]
	v_pk_mul_f32 v[82:83], v[82:83], v[188:189]
	v_pk_mul_f32 v[88:89], v[92:93], v[88:89]
	v_pk_mul_f32 v[80:81], v[84:85], v[80:81]
	v_pk_mul_f32 v[90:91], v[94:95], v[90:91]
	v_pk_mul_f32 v[82:83], v[86:87], v[82:83]
	v_cvt_pk_bf16_f32 v200, v88, v89
	v_cvt_pk_bf16_f32 v202, v80, v81
	v_cvt_pk_bf16_f32 v201, v90, v91
	v_cvt_pk_bf16_f32 v203, v82, v83
	v_add_u32_e32 v210, 0x80, v141
	v_add_u32_e32 v211, 0x2c080, v141
	global_store_dwordx2 v210, v[200:201], s[10:11]
	global_store_dwordx2 v211, v[202:203], s[10:11]
	v_pk_mul_f32 v[72:73], v[166:167], v[72:73] op_sel_hi:[0,1]
	v_pk_mul_f32 v[64:65], v[168:169], v[64:65] op_sel_hi:[0,1]
	v_pk_mul_f32 v[74:75], v[166:167], v[74:75] op_sel_hi:[0,1]
	v_pk_mul_f32 v[66:67], v[168:169], v[66:67] op_sel_hi:[0,1]
	v_pk_mul_f32 v[76:77], v[166:167], v[76:77] op_sel_hi:[0,1]
	v_pk_mul_f32 v[68:69], v[168:169], v[68:69] op_sel_hi:[0,1]
	v_pk_mul_f32 v[78:79], v[166:167], v[78:79] op_sel_hi:[0,1]
	v_pk_mul_f32 v[70:71], v[168:169], v[70:71] op_sel_hi:[0,1]
	v_pk_mul_f32 v[190:191], v[158:159], v[72:73] op_sel_hi:[0,1]
	v_pk_mul_f32 v[194:195], v[158:159], v[64:65] op_sel_hi:[0,1]
	v_pk_mul_f32 v[192:193], v[158:159], v[74:75] op_sel_hi:[0,1]
	v_pk_mul_f32 v[196:197], v[158:159], v[66:67] op_sel_hi:[0,1]
	v_exp_f32_e32 v190, v190
	v_exp_f32_e32 v194, v194
	v_exp_f32_e32 v191, v191
	v_exp_f32_e32 v195, v195
	v_exp_f32_e32 v192, v192
	v_exp_f32_e32 v196, v196
	v_exp_f32_e32 v193, v193
	v_exp_f32_e32 v197, v197
	v_pk_add_f32 v[190:191], v[160:161], v[190:191] op_sel_hi:[0,1]
	v_pk_add_f32 v[194:195], v[160:161], v[194:195] op_sel_hi:[0,1]
	v_pk_add_f32 v[192:193], v[160:161], v[192:193] op_sel_hi:[0,1]
	v_pk_add_f32 v[196:197], v[160:161], v[196:197] op_sel_hi:[0,1]
	v_rcp_f32_e32 v190, v190
	v_rcp_f32_e32 v194, v194
	v_rcp_f32_e32 v191, v191
	v_rcp_f32_e32 v195, v195
	v_rcp_f32_e32 v192, v192
	v_rcp_f32_e32 v196, v196
	v_rcp_f32_e32 v193, v193
	v_rcp_f32_e32 v197, v197
	v_pk_mul_f32 v[72:73], v[72:73], v[190:191]
	v_pk_mul_f32 v[64:65], v[64:65], v[194:195]
	v_pk_mul_f32 v[74:75], v[74:75], v[192:193]
	v_pk_mul_f32 v[66:67], v[66:67], v[196:197]
	v_pk_mul_f32 v[72:73], v[76:77], v[72:73]
	v_pk_mul_f32 v[64:65], v[68:69], v[64:65]
	v_pk_mul_f32 v[74:75], v[78:79], v[74:75]
	v_pk_mul_f32 v[66:67], v[70:71], v[66:67]
	v_cvt_pk_bf16_f32 v204, v72, v73
	v_cvt_pk_bf16_f32 v206, v64, v65
	v_cvt_pk_bf16_f32 v205, v74, v75
	v_cvt_pk_bf16_f32 v207, v66, v67
	v_add_u32_e32 v212, 0x58080, v141
	v_add_u32_e32 v213, 0x84080, v141
	global_store_dwordx2 v212, v[204:205], s[10:11]
	global_store_dwordx2 v213, v[206:207], s[10:11]
	v_pk_mul_f32 v[56:57], v[170:171], v[56:57] op_sel_hi:[0,1]
	v_pk_mul_f32 v[48:49], v[172:173], v[48:49] op_sel_hi:[0,1]
	v_pk_mul_f32 v[58:59], v[170:171], v[58:59] op_sel_hi:[0,1]
	v_pk_mul_f32 v[50:51], v[172:173], v[50:51] op_sel_hi:[0,1]
	v_pk_mul_f32 v[60:61], v[170:171], v[60:61] op_sel_hi:[0,1]
	v_pk_mul_f32 v[52:53], v[172:173], v[52:53] op_sel_hi:[0,1]
	v_pk_mul_f32 v[62:63], v[170:171], v[62:63] op_sel_hi:[0,1]
	v_pk_mul_f32 v[54:55], v[172:173], v[54:55] op_sel_hi:[0,1]
	v_pk_mul_f32 v[182:183], v[158:159], v[56:57] op_sel_hi:[0,1]
	v_pk_mul_f32 v[186:187], v[158:159], v[48:49] op_sel_hi:[0,1]
	v_pk_mul_f32 v[184:185], v[158:159], v[58:59] op_sel_hi:[0,1]
	v_pk_mul_f32 v[188:189], v[158:159], v[50:51] op_sel_hi:[0,1]
	v_exp_f32_e32 v182, v182
	v_exp_f32_e32 v186, v186
	v_exp_f32_e32 v183, v183
	v_exp_f32_e32 v187, v187
	v_exp_f32_e32 v184, v184
	v_exp_f32_e32 v188, v188
	v_exp_f32_e32 v185, v185
	v_exp_f32_e32 v189, v189
	v_pk_add_f32 v[182:183], v[160:161], v[182:183] op_sel_hi:[0,1]
	v_pk_add_f32 v[186:187], v[160:161], v[186:187] op_sel_hi:[0,1]
	v_pk_add_f32 v[184:185], v[160:161], v[184:185] op_sel_hi:[0,1]
	v_pk_add_f32 v[188:189], v[160:161], v[188:189] op_sel_hi:[0,1]
	v_rcp_f32_e32 v182, v182
	v_rcp_f32_e32 v186, v186
	v_rcp_f32_e32 v183, v183
	v_rcp_f32_e32 v187, v187
	v_rcp_f32_e32 v184, v184
	v_rcp_f32_e32 v188, v188
	v_rcp_f32_e32 v185, v185
	v_rcp_f32_e32 v189, v189
	v_pk_mul_f32 v[56:57], v[56:57], v[182:183]
	v_pk_mul_f32 v[48:49], v[48:49], v[186:187]
	v_pk_mul_f32 v[58:59], v[58:59], v[184:185]
	v_pk_mul_f32 v[50:51], v[50:51], v[188:189]
	v_pk_mul_f32 v[56:57], v[60:61], v[56:57]
	v_pk_mul_f32 v[48:49], v[52:53], v[48:49]
; __device__ __forceinline__ float silu_f(float x) { return x * __builtin_amdgcn_rcpf(1.f + __builtin_amdgcn_exp2f(-1.4426950408889634f * x)); }
; template <int EPI>
; __device__ __forceinline__ void gemm_epi(const GemmArgs& G, const f32x4 (&a)[4][2], int rbase, int cbase, int fq, const float (&ssv)[4]) {
;     ...
;   for (int m = 0; m < 4; ++m) {
;     const int row = rbase + m * 16;
;     float rs = 1.f;
;     if constexpr (EPI == EPI_GU || EPI == EPI_EVIN || EPI == EPI_ODIN) rs = rsqrtf(ssv[m] * (1.f / 2048.f) + 1e-6f);
;     if constexpr (EPI == EPI_GU) {
;       const f32x4 gv = a[m][0] * rs, uv = a[m][1] * rs;
;       const int hc = (cbase >> 1) + fq * 4;
;       u32x2 o = {cvtpk(silu_f(gv[0]) * uv[0], silu_f(gv[1]) * uv[1]), cvtpk(silu_f(gv[2]) * uv[2], silu_f(gv[3]) * uv[3])};
;       *reinterpret_cast<u32x2*>(G.d0 + (size_t)(row - G.row0) * DFF + hc) = o;
	v_pk_mul_f32 v[58:59], v[62:63], v[58:59]
	v_pk_mul_f32 v[50:51], v[54:55], v[50:51]
	v_cvt_pk_bf16_f32 v200, v56, v57
	v_cvt_pk_bf16_f32 v202, v48, v49
	v_cvt_pk_bf16_f32 v201, v58, v59
	v_cvt_pk_bf16_f32 v203, v50, v51
	v_add_u32_e32 v210, 0x160000, v141
	v_add_u32_e32 v211, 0x18c000, v141
	global_store_dwordx2 v210, v[200:201], s[10:11]
	global_store_dwordx2 v211, v[202:203], s[10:11]
	v_pk_mul_f32 v[40:41], v[174:175], v[40:41] op_sel_hi:[0,1]
	v_pk_mul_f32 v[32:33], v[176:177], v[32:33] op_sel_hi:[0,1]
	v_pk_mul_f32 v[42:43], v[174:175], v[42:43] op_sel_hi:[0,1]
	v_pk_mul_f32 v[34:35], v[176:177], v[34:35] op_sel_hi:[0,1]
	v_pk_mul_f32 v[44:45], v[174:175], v[44:45] op_sel_hi:[0,1]
	v_pk_mul_f32 v[36:37], v[176:177], v[36:37] op_sel_hi:[0,1]
	v_pk_mul_f32 v[46:47], v[174:175], v[46:47] op_sel_hi:[0,1]
	v_pk_mul_f32 v[38:39], v[176:177], v[38:39] op_sel_hi:[0,1]
	v_pk_mul_f32 v[190:191], v[158:159], v[40:41] op_sel_hi:[0,1]
	v_pk_mul_f32 v[194:195], v[158:159], v[32:33] op_sel_hi:[0,1]
	v_pk_mul_f32 v[192:193], v[158:159], v[42:43] op_sel_hi:[0,1]
	v_pk_mul_f32 v[196:197], v[158:159], v[34:35] op_sel_hi:[0,1]
	v_exp_f32_e32 v190, v190
	v_exp_f32_e32 v194, v194
	v_exp_f32_e32 v191, v191
	v_exp_f32_e32 v195, v195
	v_exp_f32_e32 v192, v192
	v_exp_f32_e32 v196, v196
	v_exp_f32_e32 v193, v193
	v_exp_f32_e32 v197, v197
	v_pk_add_f32 v[190:191], v[160:161], v[190:191] op_sel_hi:[0,1]
	v_pk_add_f32 v[194:195], v[160:161], v[194:195] op_sel_hi:[0,1]
	v_pk_add_f32 v[192:193], v[160:161], v[192:193] op_sel_hi:[0,1]
	v_pk_add_f32 v[196:197], v[160:161], v[196:197] op_sel_hi:[0,1]
	v_rcp_f32_e32 v190, v190
	v_rcp_f32_e32 v194, v194
	v_rcp_f32_e32 v191, v191
	v_rcp_f32_e32 v195, v195
	v_rcp_f32_e32 v192, v192
	v_rcp_f32_e32 v196, v196
	v_rcp_f32_e32 v193, v193
	v_rcp_f32_e32 v197, v197
	v_pk_mul_f32 v[40:41], v[40:41], v[190:191]
	v_pk_mul_f32 v[32:33], v[32:33], v[194:195]
	v_pk_mul_f32 v[42:43], v[42:43], v[192:193]
	v_pk_mul_f32 v[34:35], v[34:35], v[196:197]
	v_pk_mul_f32 v[40:41], v[44:45], v[40:41]
	v_pk_mul_f32 v[32:33], v[36:37], v[32:33]
	v_pk_mul_f32 v[42:43], v[46:47], v[42:43]
	v_pk_mul_f32 v[34:35], v[38:39], v[34:35]
	v_cvt_pk_bf16_f32 v204, v40, v41
	v_cvt_pk_bf16_f32 v206, v32, v33
	v_cvt_pk_bf16_f32 v205, v42, v43
	v_cvt_pk_bf16_f32 v207, v34, v35
	v_add_u32_e32 v212, 0x1b8000, v141
	v_add_u32_e32 v213, 0x1e4000, v141
	global_store_dwordx2 v212, v[204:205], s[10:11]
	global_store_dwordx2 v213, v[206:207], s[10:11]
	v_pk_mul_f32 v[24:25], v[170:171], v[24:25] op_sel_hi:[0,1]
	v_pk_mul_f32 v[16:17], v[172:173], v[16:17] op_sel_hi:[0,1]
	v_pk_mul_f32 v[26:27], v[170:171], v[26:27] op_sel_hi:[0,1]
	v_pk_mul_f32 v[18:19], v[172:173], v[18:19] op_sel_hi:[0,1]
	v_pk_mul_f32 v[28:29], v[170:171], v[28:29] op_sel_hi:[0,1]
	v_pk_mul_f32 v[20:21], v[172:173], v[20:21] op_sel_hi:[0,1]
	v_pk_mul_f32 v[30:31], v[170:171], v[30:31] op_sel_hi:[0,1]
	v_pk_mul_f32 v[22:23], v[172:173], v[22:23] op_sel_hi:[0,1]
	v_pk_mul_f32 v[182:183], v[158:159], v[24:25] op_sel_hi:[0,1]
	v_pk_mul_f32 v[186:187], v[158:159], v[16:17] op_sel_hi:[0,1]
	v_pk_mul_f32 v[184:185], v[158:159], v[26:27] op_sel_hi:[0,1]
	v_pk_mul_f32 v[188:189], v[158:159], v[18:19] op_sel_hi:[0,1]
	v_exp_f32_e32 v182, v182
	v_exp_f32_e32 v186, v186
	v_exp_f32_e32 v183, v183
	v_exp_f32_e32 v187, v187
	v_exp_f32_e32 v184, v184
	v_exp_f32_e32 v188, v188
	v_exp_f32_e32 v185, v185
	v_exp_f32_e32 v189, v189
	v_pk_add_f32 v[182:183], v[160:161], v[182:183] op_sel_hi:[0,1]
	v_pk_add_f32 v[186:187], v[160:161], v[186:187] op_sel_hi:[0,1]
	v_pk_add_f32 v[184:185], v[160:161], v[184:185] op_sel_hi:[0,1]
	v_pk_add_f32 v[188:189], v[160:161], v[188:189] op_sel_hi:[0,1]
	v_rcp_f32_e32 v182, v182
	v_rcp_f32_e32 v186, v186
	v_rcp_f32_e32 v183, v183
	v_rcp_f32_e32 v187, v187
	v_rcp_f32_e32 v184, v184
	v_rcp_f32_e32 v188, v188
	v_rcp_f32_e32 v185, v185
	v_rcp_f32_e32 v189, v189
	v_pk_mul_f32 v[24:25], v[24:25], v[182:183]
	v_pk_mul_f32 v[16:17], v[16:17], v[186:187]
	v_pk_mul_f32 v[26:27], v[26:27], v[184:185]
	v_pk_mul_f32 v[18:19], v[18:19], v[188:189]
	v_pk_mul_f32 v[24:25], v[28:29], v[24:25]
	v_pk_mul_f32 v[16:17], v[20:21], v[16:17]
	v_pk_mul_f32 v[26:27], v[30:31], v[26:27]
	v_pk_mul_f32 v[18:19], v[22:23], v[18:19]
	v_cvt_pk_bf16_f32 v200, v24, v25
	v_cvt_pk_bf16_f32 v202, v16, v17
	v_cvt_pk_bf16_f32 v201, v26, v27
	v_cvt_pk_bf16_f32 v203, v18, v19
	v_add_u32_e32 v210, 0x160080, v141
	v_add_u32_e32 v211, 0x18c080, v141
	global_store_dwordx2 v210, v[200:201], s[10:11]
	global_store_dwordx2 v211, v[202:203], s[10:11]
	v_pk_mul_f32 v[8:9], v[174:175], v[8:9] op_sel_hi:[0,1]
	v_pk_mul_f32 v[0:1], v[176:177], v[0:1] op_sel_hi:[0,1]
	v_pk_mul_f32 v[10:11], v[174:175], v[10:11] op_sel_hi:[0,1]
	v_pk_mul_f32 v[2:3], v[176:177], v[2:3] op_sel_hi:[0,1]
	v_pk_mul_f32 v[12:13], v[174:175], v[12:13] op_sel_hi:[0,1]
	v_pk_mul_f32 v[4:5], v[176:177], v[4:5] op_sel_hi:[0,1]
	v_pk_mul_f32 v[14:15], v[174:175], v[14:15] op_sel_hi:[0,1]
	v_pk_mul_f32 v[6:7], v[176:177], v[6:7] op_sel_hi:[0,1]
	v_pk_mul_f32 v[190:191], v[158:159], v[8:9] op_sel_hi:[0,1]
	v_pk_mul_f32 v[194:195], v[158:159], v[0:1] op_sel_hi:[0,1]
	v_pk_mul_f32 v[192:193], v[158:159], v[10:11] op_sel_hi:[0,1]
	v_pk_mul_f32 v[196:197], v[158:159], v[2:3] op_sel_hi:[0,1]
	v_exp_f32_e32 v190, v190
	v_exp_f32_e32 v194, v194
	v_exp_f32_e32 v191, v191
	v_exp_f32_e32 v195, v195
	v_exp_f32_e32 v192, v192
	v_exp_f32_e32 v196, v196
	v_exp_f32_e32 v193, v193
	v_exp_f32_e32 v197, v197
	v_pk_add_f32 v[190:191], v[160:161], v[190:191] op_sel_hi:[0,1]
	v_pk_add_f32 v[194:195], v[160:161], v[194:195] op_sel_hi:[0,1]
	v_pk_add_f32 v[192:193], v[160:161], v[192:193] op_sel_hi:[0,1]
	v_pk_add_f32 v[196:197], v[160:161], v[196:197] op_sel_hi:[0,1]
	v_rcp_f32_e32 v190, v190
	v_rcp_f32_e32 v194, v194
	v_rcp_f32_e32 v191, v191
	v_rcp_f32_e32 v195, v195
	v_rcp_f32_e32 v192, v192
	v_rcp_f32_e32 v196, v196
	v_rcp_f32_e32 v193, v193
	v_rcp_f32_e32 v197, v197
	v_pk_mul_f32 v[8:9], v[8:9], v[190:191]
	v_pk_mul_f32 v[0:1], v[0:1], v[194:195]
	v_pk_mul_f32 v[10:11], v[10:11], v[192:193]
	v_pk_mul_f32 v[2:3], v[2:3], v[196:197]
	v_pk_mul_f32 v[8:9], v[12:13], v[8:9]
	v_pk_mul_f32 v[0:1], v[4:5], v[0:1]
	v_pk_mul_f32 v[10:11], v[14:15], v[10:11]
	v_pk_mul_f32 v[2:3], v[6:7], v[2:3]
	v_cvt_pk_bf16_f32 v204, v8, v9
	v_cvt_pk_bf16_f32 v206, v0, v1
	v_cvt_pk_bf16_f32 v205, v10, v11
	v_cvt_pk_bf16_f32 v207, v2, v3
	v_add_u32_e32 v212, 0x1b8080, v141
	v_add_u32_e32 v213, 0x1e4080, v141
	global_store_dwordx2 v212, v[204:205], s[10:11]
	global_store_dwordx2 v213, v[206:207], s[10:11]
	s_andn2_b64 vcc, exec, s[14:15]
	s_mov_b32 s18, s25
	s_cbranch_vccz .LBB0_2571
